# logits_job: forget-gate weight rows staged once in LDS (ds_read instead of 32 global loads per row), next row prefetched, loop-invariant bias loads hoisted
# speedup vs baseline: 1.0040x; 1.0040x over previous
; __device__ __forceinline__ float bflo(unsigned w) { return __uint_as_float(w << 16); }
; __device__ __forceinline__ float bfhi(unsigned w) { return __uint_as_float(w & 0xffff0000u); }
; __device__ __forceinline__ void logits_job(const Args& a, const bf16* Z, int lane, int wave) {
;     ...
;     const float* WF = (const float*)(ws + WS_WF); const float* cbf = (const float*)(ws + WS_CBF); const float* bfp = a.in[8]; float* LOGF = (float*)(ws + WS_LOGF);
;     const int gw = BID * NWAVES + wave, NGW = GRD * NWAVES;
;     for (int m = gw; m < M; m += NGW) {
;         const v2u* xr = (const v2u*)(Z + (size_t)m * D) + lane;
;         f32x4 v[4]; float s = 0.f;
; #pragma unroll
;         for (int j = 0; j < 4; ++j) { const v2u w = xr[64 * j]; v[j] = (f32x4){bflo(w.x), bfhi(w.x), bflo(w.y), bfhi(w.y)}; s += (v[j][0] + v[j][1]) + (v[j][2] + v[j][3]); }
;         const float mean = wave_sum(s) * (1.f / D); float s2 = 0.f;
; #pragma unroll
;         for (int j = 0; j < 4; ++j) { v[j] = v[j] - mean; s2 += (v[j][0] * v[j][0] + v[j][1] * v[j][1]) + (v[j][2] * v[j][2] + v[j][3] * v[j][3]); }
;         const float rstd = 1.f / sqrtf(wave_sum(s2) * (1.f / D) + LN_EPS);
;         float mine = 0.f;
; #pragma unroll
;         for (int h = 0; h < 8; ++h) { float d = 0.f;
; #pragma unroll
;             for (int j = 0; j < 4; ++j) { const f32x4 w = ((const f32x4*)(WF + h * 1024))[64 * j + lane]; d += (v[j][0] * w[0] + v[j][1] * w[1]) + (v[j][2] * w[2] + v[j][3] * w[3]); }
;             d = wave_sum(d); if (lane == h) mine = d; }
;         if (lane < 8) { const float z = mine * rstd + cbf[lane] + bfp[lane];
.LBB0_412:
	s_cmp_lt_i32 s94, 4
	s_waitcnt lgkmcnt(0)
	s_cselect_b64 s[4:5], -1, 0
	s_cmp_gt_i32 s95, 3
	s_cselect_b64 s[6:7], -1, 0
	s_and_b64 s[4:5], s[4:5], s[6:7]
	s_andn2_b64 vcc, exec, s[4:5]
	s_cbranch_vccnz .LBB0_523
	v_mov_b32_e32 v0, v254
	s_mov_b32 s3, s2
	s_mov_b32 s14, s84
	s_mov_b64 s[10:11], s[0:1]
	s_load_dwordx2 s[24:25], s[10:11], 0xa8
	v_readfirstlane_b32 s4, v0
	s_ashr_i32 s6, s4, 6
	s_mov_b32 s8, s2
	s_waitcnt lgkmcnt(0)
	s_add_u32 s4, s24, 0x7c00000
	s_addc_u32 s5, s25, 0
	s_lshl_b32 s8, s8, 3
	s_add_i32 s6, s8, s6
	s_mov_b32 s7, s84
	s_cmpk_gt_i32 s6, 0x7fff
	s_cbranch_scc1 .LBB0_420
	v_mbcnt_lo_u32_b32 v2, -1, 0
	v_mbcnt_hi_u32_b32 v2, -1, v2
	v_and_b32_e32 v3, 64, v2
	v_add_u32_e32 v3, 64, v3
	v_xor_b32_e32 v4, 1, v2
	v_cmp_lt_i32_e32 vcc, v4, v3
	s_load_dwordx2 s[12:13], s[10:11], 0x40
	s_add_u32 s10, s24, 0x5800000
	v_cndmask_b32_e32 v4, v2, v4, vcc
	v_lshlrev_b32_e32 v85, 2, v4
	v_xor_b32_e32 v4, 2, v2
	v_cmp_lt_i32_e32 vcc, v4, v3
	v_and_b32_e32 v84, 63, v0
	s_addc_u32 s11, s25, 0
	v_cndmask_b32_e32 v4, v2, v4, vcc
	v_lshlrev_b32_e32 v86, 2, v4
	v_xor_b32_e32 v4, 4, v2
	v_cmp_lt_i32_e32 vcc, v4, v3
	s_lshl_b32 s8, s7, 3
	s_add_u32 s16, s24, 0x5740000
	v_cndmask_b32_e32 v4, v2, v4, vcc
	v_lshlrev_b32_e32 v87, 2, v4
	v_xor_b32_e32 v4, 8, v2
	v_cmp_lt_i32_e32 vcc, v4, v3
	v_lshlrev_b32_e32 v62, 3, v84
	v_mov_b32_e32 v63, 0
	v_cndmask_b32_e32 v4, v2, v4, vcc
	v_lshlrev_b32_e32 v88, 2, v4
	v_xor_b32_e32 v4, 16, v2
	v_cmp_lt_i32_e32 vcc, v4, v3
	s_addc_u32 s17, s25, 0
	v_lshl_add_u64 v[0:1], s[4:5], 0, v[62:63]
	v_cndmask_b32_e32 v4, v2, v4, vcc
	v_lshlrev_b32_e32 v89, 2, v4
	v_xor_b32_e32 v4, 32, v2
	v_cmp_lt_i32_e32 vcc, v4, v3
	v_lshlrev_b32_e32 v62, 2, v84
	v_mov_b32_e32 v65, v63
	v_cndmask_b32_e32 v2, v2, v4, vcc
	v_lshlrev_b32_e32 v90, 2, v2
	v_lshl_add_u64 v[2:3], s[24:25], 0, v[62:63]
	s_waitcnt lgkmcnt(0)
	v_lshl_add_u64 v[4:5], s[12:13], 0, v[62:63]
	v_lshlrev_b32_e32 v62, 4, v84
	s_add_u32 s12, s24, 0x5741000
	v_or_b32_e32 v64, 0x400, v62
	v_or_b32_e32 v66, 0x800, v62
	v_mov_b32_e32 v67, v63
	v_or_b32_e32 v68, 0xc00, v62
	v_mov_b32_e32 v69, v63
	s_addc_u32 s13, s25, 0
	v_lshl_add_u64 v[14:15], s[12:13], 0, v[62:63]
	v_lshl_add_u64 v[16:17], s[12:13], 0, v[64:65]
	v_lshl_add_u64 v[18:19], s[12:13], 0, v[66:67]
	v_lshl_add_u64 v[20:21], s[12:13], 0, v[68:69]
	s_add_u32 s12, s24, 0x5742000
	s_addc_u32 s13, s25, 0
	v_lshl_add_u64 v[22:23], s[12:13], 0, v[62:63]
	v_lshl_add_u64 v[24:25], s[12:13], 0, v[64:65]
	v_lshl_add_u64 v[26:27], s[12:13], 0, v[66:67]
	v_lshl_add_u64 v[28:29], s[12:13], 0, v[68:69]
	s_add_u32 s12, s24, 0x5743000
	s_addc_u32 s13, s25, 0
	v_lshl_add_u64 v[30:31], s[12:13], 0, v[62:63]
	v_lshl_add_u64 v[32:33], s[12:13], 0, v[64:65]
	v_lshl_add_u64 v[34:35], s[12:13], 0, v[66:67]
	v_lshl_add_u64 v[36:37], s[12:13], 0, v[68:69]
	s_add_u32 s12, s24, 0x5744000
	s_addc_u32 s13, s25, 0
	v_lshl_add_u64 v[38:39], s[12:13], 0, v[62:63]
	v_lshl_add_u64 v[40:41], s[12:13], 0, v[64:65]
	v_lshl_add_u64 v[42:43], s[12:13], 0, v[66:67]
	v_lshl_add_u64 v[44:45], s[12:13], 0, v[68:69]
	s_add_u32 s12, s24, 0x5745000
	s_addc_u32 s13, s25, 0
	v_lshl_add_u64 v[46:47], s[12:13], 0, v[62:63]
	v_lshl_add_u64 v[48:49], s[12:13], 0, v[64:65]
	v_lshl_add_u64 v[50:51], s[12:13], 0, v[66:67]
	v_lshl_add_u64 v[52:53], s[12:13], 0, v[68:69]
	s_add_u32 s12, s24, 0x5746000
	s_addc_u32 s13, s25, 0
	v_lshl_add_u64 v[54:55], s[12:13], 0, v[62:63]
	v_lshl_add_u64 v[56:57], s[12:13], 0, v[64:65]
	v_lshl_add_u64 v[58:59], s[12:13], 0, v[66:67]
	v_lshl_add_u64 v[60:61], s[12:13], 0, v[68:69]
	s_add_u32 s12, s24, 0x5747000
	s_mov_b64 s[18:19], 0x50000
	s_addc_u32 s13, s25, 0
	v_cmp_gt_u32_e64 s[38:39], 8, v84
	v_lshl_add_u64 v[2:3], v[2:3], 0, s[18:19]
	v_lshl_add_u64 v[6:7], s[16:17], 0, v[62:63]
	v_lshl_add_u64 v[8:9], s[16:17], 0, v[64:65]
	v_lshl_add_u64 v[10:11], s[16:17], 0, v[66:67]
	v_lshl_add_u64 v[12:13], s[16:17], 0, v[68:69]
	v_lshlrev_b32_e32 v246, 4, v254
	v_add_u32_e32 v247, 0x2000, v246
	v_add_u32_e32 v248, 0x4000, v246
	v_add_u32_e32 v249, 0x6000, v246
	global_load_dwordx4 v[238:241], v246, s[16:17]
	global_load_dwordx4 v[242:245], v247, s[16:17]
	global_load_dwordx4 v[250:253], v248, s[16:17]
	global_load_dwordx4 v[8:11], v249, s[16:17]
	s_waitcnt vmcnt(0)
	ds_write_b128 v246, v[238:241]
	ds_write_b128 v247, v[242:245]
	ds_write_b128 v248, v[250:253]
	ds_write_b128 v249, v[8:11]
	s_waitcnt lgkmcnt(0)
	s_barrier
	v_lshl_add_u64 v[62:63], s[12:13], 0, v[62:63]
	v_lshl_add_u64 v[64:65], s[12:13], 0, v[64:65]
	v_lshl_add_u64 v[66:67], s[12:13], 0, v[66:67]
	v_lshl_add_u64 v[68:69], s[12:13], 0, v[68:69]
	v_cmp_eq_u32_e64 s[40:41], 7, v84
	v_cmp_eq_u32_e64 s[42:43], 6, v84
	v_cmp_eq_u32_e64 s[44:45], 5, v84
	v_cmp_eq_u32_e64 s[46:47], 4, v84
	v_cmp_eq_u32_e64 s[48:49], 3, v84
	v_cmp_eq_u32_e64 s[50:51], 2, v84
	v_cmp_eq_u32_e64 s[52:53], 1, v84
	v_cmp_eq_u32_e64 s[54:55], 0, v84
	v_mov_b32_e32 v91, 0x3727c5ac
	v_mov_b32_e32 v92, 0x260
	s_mov_b32 s9, 0x800000
	s_mov_b32 s15, 0x3f317217
	s_mov_b32 s16, 0x7f800000
	v_mov_b32_e32 v93, 0x41b17218
	s_and_saveexec_b64 s[98:99], s[38:39]
	global_load_dword v16, v[2:3], off
	global_load_dword v17, v[4:5], off
	s_or_b64 exec, exec, s[98:99]
	v_lshlrev_b32_e32 v6, 4, v84
	s_ashr_i32 s7, s6, 31
	s_lshl_b64 s[98:99], s[6:7], 11
	v_lshl_add_u64 v[70:71], v[0:1], 0, s[98:99]
	global_load_dwordx2 v[8:9], v[70:71], off
	global_load_dwordx2 v[10:11], v[70:71], off offset:512
	global_load_dwordx2 v[12:13], v[70:71], off offset:1024
	global_load_dwordx2 v[14:15], v[70:71], off offset:1536
	s_branch .LBB0_417

; __device__ __forceinline__ float bflo(unsigned w) { return __uint_as_float(w << 16); }
; __device__ __forceinline__ float bfhi(unsigned w) { return __uint_as_float(w & 0xffff0000u); }
; __device__ __forceinline__ void logits_job(const Args& a, const bf16* Z, int lane, int wave) {
;     ...
;         const v2u* xr = (const v2u*)(Z + (size_t)m * D) + lane;
;         f32x4 v[4]; float s = 0.f;
; #pragma unroll
;         for (int j = 0; j < 4; ++j) { const v2u w = xr[64 * j]; v[j] = (f32x4){bflo(w.x), bfhi(w.x), bflo(w.y), bfhi(w.y)}; s += (v[j][0] + v[j][1]) + (v[j][2] + v[j][3]); }
;         const float mean = wave_sum(s) * (1.f / D); float s2 = 0.f;
; #pragma unroll
;         for (int j = 0; j < 4; ++j) { v[j] = v[j] - mean; s2 += (v[j][0] * v[j][0] + v[j][1] * v[j][1]) + (v[j][2] * v[j][2] + v[j][3] * v[j][3]); }
;         const float rstd = 1.f / sqrtf(wave_sum(s2) * (1.f / D) + LN_EPS);
;         float mine = 0.f;
; #pragma unroll
;         for (int h = 0; h < 8; ++h) { float d = 0.f;
; #pragma unroll
;             for (int j = 0; j < 4; ++j) { const f32x4 w = ((const f32x4*)(WF + h * 1024))[64 * j + lane]; d += (v[j][0] * w[0] + v[j][1] * w[1]) + (v[j][2] * w[2] + v[j][3] * w[3]); }
.LBB0_417:
	s_waitcnt vmcnt(0) lgkmcnt(0)
	v_mov_b32_e32 v72, v8
	v_mov_b32_e32 v73, v9
	v_mov_b32_e32 v74, v10
	v_mov_b32_e32 v75, v11
	v_mov_b32_e32 v96, v12
	v_mov_b32_e32 v97, v13
	v_mov_b32_e32 v132, v14
	v_mov_b32_e32 v133, v15
	s_add_i32 s98, s6, s8
	s_cmp_lt_i32 s98, 0x8000
	s_cselect_b32 s98, s98, s6
	s_ashr_i32 s99, s98, 31
	s_lshl_b64 s[98:99], s[98:99], 11
	v_lshl_add_u64 v[70:71], v[0:1], 0, s[98:99]
	s_ashr_i32 s7, s6, 31
	global_load_dwordx2 v[8:9], v[70:71], off
	global_load_dwordx2 v[10:11], v[70:71], off offset:512
	global_load_dwordx2 v[12:13], v[70:71], off offset:1024
	global_load_dwordx2 v[14:15], v[70:71], off offset:1536
	ds_read_b128 v[100:103], v6
	ds_read_b128 v[104:107], v6 offset:1024
	ds_read_b128 v[108:111], v6 offset:2048
	ds_read_b128 v[112:115], v6 offset:3072
	ds_read_b128 v[116:119], v6 offset:4096
	ds_read_b128 v[120:123], v6 offset:5120
	ds_read_b128 v[124:127], v6 offset:6144
	ds_read_b128 v[128:131], v6 offset:7168
	s_waitcnt lgkmcnt(0)
	v_lshlrev_b32_e32 v79, 16, v73
	v_lshlrev_b32_e32 v78, 16, v72
	v_and_b32_e32 v83, 0xffff0000, v73
	v_and_b32_e32 v82, 0xffff0000, v72
	v_lshlrev_b32_e32 v77, 16, v75
	v_lshlrev_b32_e32 v76, 16, v74
	v_and_b32_e32 v81, 0xffff0000, v75
	v_and_b32_e32 v80, 0xffff0000, v74
	v_lshlrev_b32_e32 v95, 16, v96
	v_and_b32_e32 v98, 0xffff0000, v96
	v_lshlrev_b32_e32 v73, 16, v132
	v_and_b32_e32 v96, 0xffff0000, v132
	v_lshlrev_b32_e32 v71, 16, v133
	v_and_b32_e32 v75, 0xffff0000, v133
	v_pk_add_f32 v[132:133], v[78:79], v[82:83]
	v_pk_add_f32 v[134:135], v[76:77], v[80:81]
	v_lshlrev_b32_e32 v94, 16, v97
	v_and_b32_e32 v97, 0xffff0000, v97
	v_add_f32_e32 v72, v132, v133
	v_pk_add_f32 v[132:133], v[134:135], v[134:135] op_sel:[0,1] op_sel_hi:[1,0]
	v_add_f32_e32 v70, v95, v98
	v_add_f32_e32 v74, v94, v97
	v_add_f32_e32 v72, 0, v72
	v_mov_b32_e32 v133, v96
	v_pk_add_f32 v[134:135], v[70:71], v[74:75]
	v_pk_add_f32 v[132:133], v[72:73], v[132:133]
	s_nop 0
	v_pk_add_f32 v[132:133], v[132:133], v[134:135]
	s_nop 0
	v_add_f32_e32 v70, v132, v133
	ds_read_b128 v[132:135], v6 offset:8192
	ds_read_b128 v[136:139], v6 offset:9216
	s_nop 1
	v_mov_b32_dpp v72, v70 quad_perm:[1,0,3,2] row_mask:0xf bank_mask:0xf
	ds_read_b128 v[140:143], v6 offset:10240
	ds_read_b128 v[144:147], v6 offset:11264
	ds_read_b128 v[148:151], v6 offset:12288
	ds_read_b128 v[152:155], v6 offset:13312
	ds_read_b128 v[156:159], v6 offset:14336
	s_waitcnt lgkmcnt(0)
	v_add_f32_e32 v70, v70, v72
	s_nop 1
	v_mov_b32_dpp v72, v70 quad_perm:[2,3,0,1] row_mask:0xf bank_mask:0xf
	s_waitcnt lgkmcnt(0)
	v_add_f32_e32 v70, v70, v72
	s_nop 1
	v_mov_b32_dpp v72, v70 row_shl:4 row_mask:0xf bank_mask:0x5
	v_mov_b32_dpp v72, v70 row_shr:4 row_mask:0xf bank_mask:0xa
	s_waitcnt lgkmcnt(0)
	v_add_f32_e32 v70, v70, v72
	s_nop 1
	v_mov_b32_dpp v72, v70 row_shl:8 row_mask:0xf bank_mask:0x3
	v_mov_b32_dpp v72, v70 row_shr:8 row_mask:0xf bank_mask:0xc
	s_waitcnt lgkmcnt(0)
	v_add_f32_e32 v70, v70, v72
	v_mov_b32_e32 v72, v70
	v_mov_b32_e32 v238, v70
	s_nop 1
	v_permlane16_swap_b32 v72, v238
	s_waitcnt lgkmcnt(0)
	v_add_f32_e32 v70, v238, v72
	v_mov_b32_e32 v72, v70
	v_mov_b32_e32 v239, v70
	s_nop 1
	v_permlane32_swap_b32 v72, v239
	s_waitcnt lgkmcnt(0)
	v_add_f32_e32 v70, v239, v72
	v_fmac_f32_e32 v83, 0xba800000, v70
	v_fmac_f32_e32 v82, 0xba800000, v70
	v_fmac_f32_e32 v81, 0xba800000, v70
	v_fmac_f32_e32 v80, 0xba800000, v70
	v_fmac_f32_e32 v79, 0xba800000, v70
	v_fmac_f32_e32 v78, 0xba800000, v70
	v_fmac_f32_e32 v77, 0xba800000, v70
	v_fmac_f32_e32 v76, 0xba800000, v70
	v_fmac_f32_e32 v94, 0xba800000, v70
	v_fmac_f32_e32 v97, 0xba800000, v70
	v_fmac_f32_e32 v95, 0xba800000, v70
	v_fmac_f32_e32 v98, 0xba800000, v70
	v_fmac_f32_e32 v71, 0xba800000, v70
	v_fmac_f32_e32 v75, 0xba800000, v70
	v_fmac_f32_e32 v73, 0xba800000, v70
	v_fmac_f32_e32 v96, 0xba800000, v70
	v_mul_f32_e32 v70, v82, v82
	v_mul_f32_e32 v72, v83, v83
	v_mul_f32_e32 v74, v80, v80
	v_mul_f32_e32 v99, v81, v81
	v_mul_f32_e32 v160, v98, v98
	v_mul_f32_e32 v161, v97, v97
	v_fmac_f32_e32 v70, v78, v78
	v_fmac_f32_e32 v72, v79, v79
	v_fmac_f32_e32 v74, v76, v76
	v_fmac_f32_e32 v99, v77, v77
	v_mul_f32_e32 v162, v96, v96
	v_mul_f32_e32 v163, v75, v75
	v_fmac_f32_e32 v160, v95, v95
	v_fmac_f32_e32 v161, v94, v94
	v_add_f32_e32 v70, v70, v72
	v_add_f32_e32 v72, v74, v99
	v_mul_f32_e32 v101, v101, v82
	v_mul_f32_e32 v103, v103, v83
	v_mul_f32_e32 v117, v82, v117
	v_mul_f32_e32 v119, v83, v119
	v_fmac_f32_e32 v162, v73, v73
	v_fmac_f32_e32 v163, v71, v71
	v_add_f32_e32 v74, v160, v161
	v_add_f32_e32 v70, v70, v72
	v_mul_f32_e32 v105, v105, v80
	v_mul_f32_e32 v107, v107, v81
	v_mul_f32_e32 v121, v80, v121
	v_mul_f32_e32 v123, v81, v123
	v_fmac_f32_e32 v101, v100, v78
	v_fmac_f32_e32 v103, v102, v79
	v_fmac_f32_e32 v117, v78, v116
	v_fmac_f32_e32 v119, v79, v118
	v_add_f32_e32 v99, v162, v163
	v_add_f32_e32 v70, v74, v70
	v_mul_f32_e32 v109, v109, v98
	v_mul_f32_e32 v111, v111, v97
	v_mul_f32_e32 v125, v98, v125
	v_mul_f32_e32 v127, v97, v127
	v_fmac_f32_e32 v105, v104, v76
	v_fmac_f32_e32 v107, v106, v77
	v_fmac_f32_e32 v121, v76, v120
	v_fmac_f32_e32 v123, v77, v122
	v_add_f32_e32 v100, v101, v103
	v_add_f32_e32 v70, v99, v70
	v_add_f32_e32 v99, v117, v119
	v_fmac_f32_e32 v109, v108, v95
	v_fmac_f32_e32 v111, v110, v94
	v_fmac_f32_e32 v125, v95, v124
	v_fmac_f32_e32 v127, v94, v126
	v_add_f32_e32 v101, v105, v107
	v_add_f32_e32 v103, v121, v123
	v_add_f32_e32 v100, 0, v100
	v_add_f32_e32 v99, 0, v99
	v_add_f32_e32 v102, v109, v111
	v_add_f32_e32 v104, v125, v127
	v_add_f32_e32 v100, v101, v100
	v_add_f32_e32 v99, v99, v103
	v_add_f32_e32 v100, v102, v100
	v_add_f32_e32 v99, v99, v104
	ds_read_b128 v[102:105], v6 offset:15360
	ds_read_b128 v[106:109], v6 offset:16384
	v_mul_f32_e32 v113, v96, v113
	v_mul_f32_e32 v115, v75, v115
	v_fmac_f32_e32 v113, v73, v112
	v_fmac_f32_e32 v115, v71, v114
	v_add_f32_e32 v74, v113, v115
	ds_read_b128 v[110:113], v6 offset:17408
	ds_read_b128 v[114:117], v6 offset:18432
	s_waitcnt lgkmcnt(0)
; __device__ __forceinline__ void logits_job(const Args& a, const bf16* Z, int lane, int wave) {
;     ...
;         for (int h = 0; h < 8; ++h) { float d = 0.f;
; #pragma unroll
;             for (int j = 0; j < 4; ++j) { const f32x4 w = ((const f32x4*)(WF + h * 1024))[64 * j + lane]; d += (v[j][0] * w[0] + v[j][1] * w[1]) + (v[j][2] * w[2] + v[j][3] * w[3]); }
;             d = wave_sum(d); if (lane == h) mine = d; }
	v_mul_f32_e32 v118, v82, v133
	v_mul_f32_e32 v119, v83, v135
	v_fmac_f32_e32 v118, v78, v132
	v_fmac_f32_e32 v119, v79, v134
	v_add_f32_e32 v118, v118, v119
	v_add_f32_e32 v122, 0, v118
	ds_read_b128 v[118:121], v6 offset:19456
	v_mul_f32_e32 v129, v96, v129
	v_mul_f32_e32 v101, v75, v131
	v_fmac_f32_e32 v129, v73, v128
	v_fmac_f32_e32 v101, v71, v130
	v_add_f32_e32 v101, v129, v101
	v_add_f32_e32 v74, v74, v100
	v_add_f32_e32 v99, v99, v101
	s_nop 1
	v_mov_b32_dpp v100, v74 quad_perm:[1,0,3,2] row_mask:0xf bank_mask:0xf
	s_nop 1
	v_mov_b32_dpp v101, v99 quad_perm:[1,0,3,2] row_mask:0xf bank_mask:0xf
	s_waitcnt lgkmcnt(0)
	v_mul_f32_e32 v123, v80, v137
	v_mul_f32_e32 v124, v81, v139
	v_fmac_f32_e32 v123, v76, v136
	s_waitcnt lgkmcnt(0)
	v_add_f32_e32 v74, v74, v100
	s_waitcnt lgkmcnt(0)
	v_add_f32_e32 v99, v99, v101
	s_nop 1
	v_mov_b32_dpp v100, v74 quad_perm:[2,3,0,1] row_mask:0xf bank_mask:0xf
	s_nop 1
	v_mov_b32_dpp v101, v99 quad_perm:[2,3,0,1] row_mask:0xf bank_mask:0xf
	v_fmac_f32_e32 v124, v77, v138
	v_add_f32_e32 v123, v123, v124
	v_add_f32_e32 v122, v122, v123
	s_waitcnt lgkmcnt(0)
	v_mul_f32_e32 v123, v98, v141
	v_mul_f32_e32 v124, v97, v143
	v_fmac_f32_e32 v123, v95, v140
	v_fmac_f32_e32 v124, v94, v142
	v_add_f32_e32 v123, v123, v124
	s_waitcnt lgkmcnt(0)
	v_add_f32_e32 v74, v74, v100
	s_waitcnt lgkmcnt(0)
	v_add_f32_e32 v99, v99, v101
	v_add_f32_e32 v122, v122, v123
	s_waitcnt lgkmcnt(0)
	v_mul_f32_e32 v123, v96, v145
	v_mul_f32_e32 v124, v75, v147
	s_nop 1
	v_mov_b32_dpp v100, v74 row_shl:4 row_mask:0xf bank_mask:0x5
	v_mov_b32_dpp v100, v74 row_shr:4 row_mask:0xf bank_mask:0xa
	s_nop 1
	v_mov_b32_dpp v101, v99 row_shl:4 row_mask:0xf bank_mask:0x5
	v_mov_b32_dpp v101, v99 row_shr:4 row_mask:0xf bank_mask:0xa
	v_fmac_f32_e32 v123, v73, v144
	v_fmac_f32_e32 v124, v71, v146
	v_add_f32_e32 v123, v123, v124
	v_add_f32_e32 v122, v122, v123
	s_nop 1
	v_mov_b32_dpp v123, v122 quad_perm:[1,0,3,2] row_mask:0xf bank_mask:0xf
	s_waitcnt lgkmcnt(0)
	v_add_f32_e32 v74, v74, v100
	s_waitcnt lgkmcnt(0)
	v_add_f32_e32 v99, v99, v101
	s_nop 1
	v_mov_b32_dpp v100, v74 row_shl:8 row_mask:0xf bank_mask:0x3
	v_mov_b32_dpp v100, v74 row_shr:8 row_mask:0xf bank_mask:0xc
	s_nop 1
	v_mov_b32_dpp v101, v99 row_shl:8 row_mask:0xf bank_mask:0x3
	v_mov_b32_dpp v101, v99 row_shr:8 row_mask:0xf bank_mask:0xc
	s_waitcnt lgkmcnt(0)
	v_add_f32_e32 v122, v122, v123
	s_nop 1
	v_mov_b32_dpp v123, v122 quad_perm:[2,3,0,1] row_mask:0xf bank_mask:0xf
	s_waitcnt lgkmcnt(0)
	v_mul_f32_e32 v127, v80, v153
	s_waitcnt lgkmcnt(0)
	v_add_f32_e32 v74, v74, v100
	s_waitcnt lgkmcnt(0)
	v_add_f32_e32 v101, v99, v101
	v_mov_b32_e32 v100, v74
	v_mov_b32_e32 v240, v74
	s_nop 1
	v_permlane16_swap_b32 v100, v240
	v_mov_b32_e32 v124, v101
	v_mov_b32_e32 v241, v101
	s_nop 1
	v_permlane16_swap_b32 v124, v241
	s_waitcnt lgkmcnt(0)
	v_add_f32_e32 v146, v122, v123
	v_mul_f32_e32 v122, v82, v149
	v_mul_f32_e32 v123, v83, v151
	v_fmac_f32_e32 v122, v78, v148
	v_fmac_f32_e32 v123, v79, v150
	v_add_f32_e32 v122, v122, v123
	v_mul_f32_e32 v128, v81, v155
	s_waitcnt lgkmcnt(0)
	v_add_f32_e32 v74, v240, v100
	s_waitcnt lgkmcnt(0)
	v_add_f32_e32 v100, v241, v124
	v_add_f32_e32 v126, 0, v122
	v_fmac_f32_e32 v127, v76, v152
	ds_read_b128 v[122:125], v6 offset:20480
	v_fmac_f32_e32 v128, v77, v154
	v_add_f32_e32 v127, v127, v128
	v_add_f32_e32 v130, v126, v127
	s_waitcnt lgkmcnt(0)
	v_mul_f32_e32 v131, v98, v157
	ds_read_b128 v[126:129], v6 offset:21504
	s_waitcnt lgkmcnt(0)
	v_mul_f32_e32 v103, v96, v103
	v_fmac_f32_e32 v103, v73, v102
	v_mul_f32_e32 v102, v75, v105
	v_fmac_f32_e32 v102, v71, v104
	s_waitcnt lgkmcnt(0)
	v_mul_f32_e32 v104, v82, v107
	v_mul_f32_e32 v105, v83, v109
	v_mul_f32_e32 v132, v97, v159
	v_fmac_f32_e32 v104, v78, v106
	v_fmac_f32_e32 v105, v79, v108
	v_fmac_f32_e32 v131, v95, v156
	v_fmac_f32_e32 v132, v94, v158
	v_add_f32_e32 v104, v104, v105
	s_waitcnt lgkmcnt(0)
	v_mul_f32_e32 v105, v80, v111
	v_mul_f32_e32 v106, v81, v113
	v_add_f32_e32 v131, v131, v132
	v_fmac_f32_e32 v105, v76, v110
	v_fmac_f32_e32 v106, v77, v112
	v_add_f32_e32 v138, v130, v131
	ds_read_b128 v[130:133], v6 offset:22528
	v_add_f32_e32 v104, 0, v104
	v_add_f32_e32 v105, v105, v106
	v_add_f32_e32 v104, v104, v105
	s_waitcnt lgkmcnt(0)
	v_mul_f32_e32 v105, v98, v115
	v_mul_f32_e32 v106, v97, v117
	s_nop 1
	v_mov_b32_dpp v147, v146 row_shl:4 row_mask:0xf bank_mask:0x5
	v_mov_b32_dpp v147, v146 row_shr:4 row_mask:0xf bank_mask:0xa
	v_fmac_f32_e32 v105, v95, v114
	v_fmac_f32_e32 v106, v94, v116
	ds_read_b128 v[134:137], v6 offset:23552
	v_add_f32_e32 v105, v105, v106
	v_add_f32_e32 v102, v103, v102
	v_add_f32_e32 v104, v104, v105
	s_waitcnt lgkmcnt(0)
	v_mul_f32_e32 v105, v96, v119
	v_add_f32_e32 v102, v138, v102
	ds_read_b128 v[138:141], v6 offset:24576
	ds_read_b128 v[142:145], v6 offset:27648
	v_fmac_f32_e32 v105, v73, v118
	v_mul_f32_e32 v106, v75, v121
	ds_read_b128 v[116:119], v6 offset:28672
	v_fmac_f32_e32 v106, v71, v120
	ds_read_b128 v[108:111], v6 offset:25600
	ds_read_b128 v[112:115], v6 offset:26624
	v_add_f32_e32 v105, v105, v106
	s_waitcnt lgkmcnt(0)
	v_add_f32_e32 v106, v146, v147
	ds_read_b128 v[146:149], v6 offset:29696
	ds_read_b128 v[150:153], v6 offset:30720
	ds_read_b128 v[154:157], v6 offset:31744
	s_nop 1
	v_mov_b32_dpp v103, v102 quad_perm:[1,0,3,2] row_mask:0xf bank_mask:0xf
	v_add_f32_e32 v104, v104, v105
	s_nop 1
	v_mov_b32_dpp v105, v104 quad_perm:[1,0,3,2] row_mask:0xf bank_mask:0xf
	s_nop 1
	v_mov_b32_dpp v72, v70 quad_perm:[1,0,3,2] row_mask:0xf bank_mask:0xf
	s_nop 1
	v_mov_b32_dpp v107, v106 row_shl:8 row_mask:0xf bank_mask:0x3
	v_mov_b32_dpp v107, v106 row_shr:8 row_mask:0xf bank_mask:0xc
	s_waitcnt lgkmcnt(0)
; __device__ __forceinline__ void logits_job(const Args& a, const bf16* Z, int lane, int wave) {
;     ...
;         for (int h = 0; h < 8; ++h) { float d = 0.f;
; #pragma unroll
;             for (int j = 0; j < 4; ++j) { const f32x4 w = ((const f32x4*)(WF + h * 1024))[64 * j + lane]; d += (v[j][0] * w[0] + v[j][1] * w[1]) + (v[j][2] * w[2] + v[j][3] * w[3]); }
;             d = wave_sum(d); if (lane == h) mine = d; }
	v_add_f32_e32 v102, v102, v103
	s_nop 1
	v_mov_b32_dpp v103, v102 quad_perm:[2,3,0,1] row_mask:0xf bank_mask:0xf
	s_waitcnt lgkmcnt(0)
	v_add_f32_e32 v104, v104, v105
	s_nop 1
	v_mov_b32_dpp v105, v104 quad_perm:[2,3,0,1] row_mask:0xf bank_mask:0xf
	s_waitcnt lgkmcnt(0)
	v_add_f32_e32 v70, v70, v72
	s_nop 1
	v_mov_b32_dpp v72, v70 quad_perm:[2,3,0,1] row_mask:0xf bank_mask:0xf
	s_waitcnt lgkmcnt(0)
	v_add_f32_e32 v102, v102, v103
	s_nop 1
	v_mov_b32_dpp v103, v102 row_shl:4 row_mask:0xf bank_mask:0x5
	v_mov_b32_dpp v103, v102 row_shr:4 row_mask:0xf bank_mask:0xa
	s_waitcnt lgkmcnt(0)
	v_add_f32_e32 v104, v104, v105
	s_nop 1
	v_mov_b32_dpp v105, v104 row_shl:4 row_mask:0xf bank_mask:0x5
	v_mov_b32_dpp v105, v104 row_shr:4 row_mask:0xf bank_mask:0xa
	s_waitcnt lgkmcnt(0)
	v_add_f32_e32 v70, v70, v72
	s_nop 1
	v_mov_b32_dpp v72, v70 row_shl:4 row_mask:0xf bank_mask:0x5
	v_mov_b32_dpp v72, v70 row_shr:4 row_mask:0xf bank_mask:0xa
	s_waitcnt lgkmcnt(0)
	v_add_f32_e32 v102, v102, v103
	s_nop 1
	v_mov_b32_dpp v103, v102 row_shl:8 row_mask:0xf bank_mask:0x3
	v_mov_b32_dpp v103, v102 row_shr:8 row_mask:0xf bank_mask:0xc
	s_waitcnt lgkmcnt(0)
	v_add_f32_e32 v104, v104, v105
	s_nop 1
	v_mov_b32_dpp v105, v104 row_shl:8 row_mask:0xf bank_mask:0x3
	v_mov_b32_dpp v105, v104 row_shr:8 row_mask:0xf bank_mask:0xc
	s_waitcnt lgkmcnt(0)
	v_add_f32_e32 v70, v70, v72
	s_nop 1
	v_mov_b32_dpp v72, v70 row_shl:8 row_mask:0xf bank_mask:0x3
	v_mov_b32_dpp v72, v70 row_shr:8 row_mask:0xf bank_mask:0xc
	s_waitcnt lgkmcnt(0)
	v_add_f32_e32 v120, v102, v103
	v_mov_b32_e32 v121, v120
	v_mov_b32_e32 v242, v120
	s_nop 1
	v_permlane16_swap_b32 v121, v242
	s_waitcnt lgkmcnt(0)
	v_add_f32_e32 v158, v104, v105
	v_add_f32_e32 v106, v106, v107
	s_waitcnt lgkmcnt(0)
	v_add_f32_e32 v70, v70, v72
	v_mov_b32_e32 v72, v70
	v_mov_b32_e32 v243, v70
	s_nop 1
	v_permlane16_swap_b32 v72, v243
	s_waitcnt lgkmcnt(0)
	v_add_f32_e32 v104, v242, v121
	s_waitcnt lgkmcnt(0)
	v_mul_f32_e32 v120, v82, v123
	v_mul_f32_e32 v121, v83, v125
	v_fmac_f32_e32 v120, v78, v122
	v_fmac_f32_e32 v121, v79, v124
	v_add_f32_e32 v120, v120, v121
	s_waitcnt lgkmcnt(0)
	v_mul_f32_e32 v121, v80, v127
	v_mul_f32_e32 v122, v81, v129
	v_fmac_f32_e32 v121, v76, v126
	v_fmac_f32_e32 v122, v77, v128
	v_add_f32_e32 v120, 0, v120
	v_add_f32_e32 v121, v121, v122
	v_add_f32_e32 v120, v120, v121
	v_mov_b32_e32 v107, v106
	v_mov_b32_e32 v244, v106
	s_nop 1
	v_permlane16_swap_b32 v107, v244
	v_mov_b32_e32 v159, v158
	v_mov_b32_e32 v245, v158
	s_nop 1
	v_permlane16_swap_b32 v159, v245
	s_waitcnt lgkmcnt(0)
	v_add_f32_e32 v70, v243, v72
	ds_bpermute_b32 v72, v90, v70
	ds_bpermute_b32 v99, v90, v74
	s_waitcnt lgkmcnt(0)
	v_add_f32_e32 v102, v244, v107
	s_waitcnt lgkmcnt(0)
	v_add_f32_e32 v106, v245, v159
	ds_bpermute_b32 v101, v90, v100
	ds_bpermute_b32 v103, v90, v102
	ds_bpermute_b32 v105, v90, v104
	s_waitcnt lgkmcnt(0)
	v_mul_f32_e32 v121, v98, v131
	v_mul_f32_e32 v122, v97, v133
	v_fmac_f32_e32 v121, v95, v130
	v_fmac_f32_e32 v122, v94, v132
	v_add_f32_e32 v121, v121, v122
	v_add_f32_e32 v120, v120, v121
	ds_bpermute_b32 v107, v90, v106
	s_waitcnt lgkmcnt(0)
	v_mul_f32_e32 v121, v96, v135
	v_mul_f32_e32 v122, v75, v137
	v_fmac_f32_e32 v121, v73, v134
	v_fmac_f32_e32 v122, v71, v136
	v_add_f32_e32 v121, v121, v122
	v_add_f32_e32 v120, v120, v121
	s_waitcnt lgkmcnt(0)
	v_mul_f32_e32 v122, v82, v139
	v_fmac_f32_e32 v122, v78, v138
	v_mul_f32_e32 v123, v83, v141
	v_fmac_f32_e32 v123, v79, v140
	s_waitcnt lgkmcnt(0)
	v_mul_f32_e32 v82, v82, v117
	v_fmac_f32_e32 v82, v78, v116
	v_mul_f32_e32 v78, v83, v119
	s_waitcnt lgkmcnt(0)
	v_mul_f32_e32 v109, v80, v109
	v_fmac_f32_e32 v78, v79, v118
	v_fmac_f32_e32 v109, v76, v108
	s_waitcnt lgkmcnt(0)
	v_mul_f32_e32 v79, v80, v147
	v_fmac_f32_e32 v79, v76, v146
	v_mul_f32_e32 v76, v81, v149
	v_mul_f32_e32 v108, v81, v111
	v_add_f32_e32 v78, v82, v78
	v_fmac_f32_e32 v76, v77, v148
	v_fmac_f32_e32 v108, v77, v110
	v_add_f32_e32 v78, 0, v78
	v_add_f32_e32 v76, v79, v76
	v_add_f32_e32 v122, v122, v123
	v_add_f32_e32 v108, v109, v108
	v_mul_f32_e32 v109, v98, v113
	v_mul_f32_e32 v110, v97, v115
	v_add_f32_e32 v76, v78, v76
	s_waitcnt lgkmcnt(0)
	v_mul_f32_e32 v77, v98, v151
	v_mul_f32_e32 v78, v97, v153
	v_add_f32_e32 v122, 0, v122
	v_fmac_f32_e32 v109, v95, v112
	v_fmac_f32_e32 v110, v94, v114
	v_fmac_f32_e32 v77, v95, v150
	v_fmac_f32_e32 v78, v94, v152
	v_add_f32_e32 v108, v122, v108
	v_add_f32_e32 v109, v109, v110
	v_add_f32_e32 v77, v77, v78
	v_add_f32_e32 v108, v108, v109
	v_mul_f32_e32 v109, v96, v143
	v_add_f32_e32 v76, v76, v77
	s_waitcnt lgkmcnt(0)
	v_mul_f32_e32 v77, v96, v155
	v_fmac_f32_e32 v109, v73, v142
	v_mul_f32_e32 v110, v75, v145
	v_fmac_f32_e32 v77, v73, v154
	v_mul_f32_e32 v73, v75, v157
	v_fmac_f32_e32 v110, v71, v144
	v_fmac_f32_e32 v73, v71, v156
	v_add_f32_e32 v109, v109, v110
	v_add_f32_e32 v71, v77, v73
	v_add_f32_e32 v108, v108, v109
	v_add_f32_e32 v71, v76, v71
	s_nop 1
	v_mov_b32_dpp v121, v120 quad_perm:[1,0,3,2] row_mask:0xf bank_mask:0xf
	s_nop 1
	v_mov_b32_dpp v109, v108 quad_perm:[1,0,3,2] row_mask:0xf bank_mask:0xf
	s_nop 1
	v_mov_b32_dpp v73, v71 quad_perm:[1,0,3,2] row_mask:0xf bank_mask:0xf
	s_waitcnt lgkmcnt(0)
	v_add_f32_e32 v75, v120, v121
	s_waitcnt lgkmcnt(0)
	v_add_f32_e32 v77, v108, v109
	s_waitcnt lgkmcnt(0)
; __device__ __forceinline__ void logits_job(const Args& a, const bf16* Z, int lane, int wave) {
;     ...
;             d = wave_sum(d); if (lane == h) mine = d; }
;         if (lane < 8) { const float z = mine * rstd + cbf[lane] + bfp[lane];
;             const float e_ = __expf(-fabsf(z)), u_ = 1.f + e_; const float l1p = (u_ == 1.f) ? e_ : __logf(u_) * (e_ / (u_ - 1.f));
;             const float ls = fminf(z, 0.f) - l1p;
;             const int b = m / S, sidx = m % S; LOGF[((size_t)(b * 8 + lane)) * S + sidx] = ls; }
;     }
	v_add_f32_e32 v71, v71, v73
	s_nop 1
	v_mov_b32_dpp v76, v75 quad_perm:[2,3,0,1] row_mask:0xf bank_mask:0xf
	s_nop 1
	v_mov_b32_dpp v78, v77 quad_perm:[2,3,0,1] row_mask:0xf bank_mask:0xf
	s_nop 1
	v_mov_b32_dpp v73, v71 quad_perm:[2,3,0,1] row_mask:0xf bank_mask:0xf
	s_waitcnt lgkmcnt(0)
	v_add_f32_e32 v75, v75, v76
	s_waitcnt lgkmcnt(0)
	v_add_f32_e32 v77, v77, v78
	s_waitcnt lgkmcnt(0)
	v_add_f32_e32 v71, v71, v73
	s_nop 1
	v_mov_b32_dpp v76, v75 row_shl:4 row_mask:0xf bank_mask:0x5
	v_mov_b32_dpp v76, v75 row_shr:4 row_mask:0xf bank_mask:0xa
	s_nop 1
	v_mov_b32_dpp v78, v77 row_shl:4 row_mask:0xf bank_mask:0x5
	v_mov_b32_dpp v78, v77 row_shr:4 row_mask:0xf bank_mask:0xa
	s_nop 1
	v_mov_b32_dpp v73, v71 row_shl:4 row_mask:0xf bank_mask:0x5
	v_mov_b32_dpp v73, v71 row_shr:4 row_mask:0xf bank_mask:0xa
	s_waitcnt lgkmcnt(0)
	v_add_f32_e32 v75, v75, v76
	s_waitcnt lgkmcnt(0)
	v_add_f32_e32 v77, v77, v78
	s_waitcnt lgkmcnt(0)
	v_add_f32_e32 v71, v71, v73
	s_nop 1
	v_mov_b32_dpp v76, v75 row_shl:8 row_mask:0xf bank_mask:0x3
	v_mov_b32_dpp v76, v75 row_shr:8 row_mask:0xf bank_mask:0xc
	s_nop 1
	v_mov_b32_dpp v78, v77 row_shl:8 row_mask:0xf bank_mask:0x3
	v_mov_b32_dpp v78, v77 row_shr:8 row_mask:0xf bank_mask:0xc
	s_nop 1
	v_mov_b32_dpp v73, v71 row_shl:8 row_mask:0xf bank_mask:0x3
	v_mov_b32_dpp v73, v71 row_shr:8 row_mask:0xf bank_mask:0xc
	s_waitcnt lgkmcnt(0)
	v_add_f32_e32 v75, v75, v76
	s_waitcnt lgkmcnt(0)
	v_add_f32_e32 v77, v77, v78
	s_waitcnt lgkmcnt(0)
	v_add_f32_e32 v79, v71, v73
	v_mov_b32_e32 v76, v75
	v_mov_b32_e32 v246, v75
	s_nop 1
	v_permlane16_swap_b32 v76, v246
	v_mov_b32_e32 v78, v77
	v_mov_b32_e32 v247, v77
	s_nop 1
	v_permlane16_swap_b32 v78, v247
	v_mov_b32_e32 v80, v79
	v_mov_b32_e32 v248, v79
	s_nop 1
	v_permlane16_swap_b32 v80, v248
	s_waitcnt lgkmcnt(0)
	v_add_f32_e32 v71, v246, v76
	s_waitcnt lgkmcnt(0)
	v_add_f32_e32 v75, v247, v78
	s_waitcnt lgkmcnt(0)
	v_add_f32_e32 v77, v248, v80
	v_mov_b32_e32 v73, v71
	v_mov_b32_e32 v249, v71
	s_nop 1
	v_permlane32_swap_b32 v73, v249
	v_mov_b32_e32 v76, v75
	v_mov_b32_e32 v250, v75
	s_nop 1
	v_permlane32_swap_b32 v76, v250
	v_mov_b32_e32 v78, v77
	v_mov_b32_e32 v251, v77
	s_nop 1
	v_permlane32_swap_b32 v78, v251
	s_and_saveexec_b64 s[12:13], s[38:39]
	s_cbranch_execz .LBB0_416
	v_mov_b32_e32 v79, v16
	v_mov_b32_e32 v80, v17
	v_add_f32_e32 v70, v70, v72
	s_mov_b32 s17, 0xf800000
	v_add_f32_e32 v74, v74, v99
	v_fmamk_f32 v70, v70, 0x3a800000, v91
	s_waitcnt lgkmcnt(0)
	v_add_f32_e32 v72, v251, v78
	v_add_f32_e32 v78, v100, v101
	v_cndmask_b32_e64 v74, 0, v74, s[54:55]
	v_mul_f32_e32 v81, 0x4f800000, v70
	v_cmp_gt_f32_e32 vcc, s17, v70
	v_add_f32_e32 v77, v102, v103
	v_cndmask_b32_e64 v74, v74, v78, s[52:53]
	v_cndmask_b32_e32 v70, v70, v81, vcc
	v_cndmask_b32_e64 v74, v74, v77, s[50:51]
	v_sqrt_f32_e32 v77, v70
	v_add_f32_e32 v75, v250, v76
	v_add_f32_e32 v76, v104, v105
	v_add_f32_e32 v71, v249, v73
	v_add_f32_e32 v73, v106, v107
	v_cndmask_b32_e64 v74, v74, v76, s[48:49]
	v_cndmask_b32_e64 v73, v74, v73, s[46:47]
	v_cndmask_b32_e64 v71, v73, v71, s[44:45]
	v_add_u32_e32 v73, -1, v77
	v_cndmask_b32_e64 v71, v71, v75, s[42:43]
	v_add_u32_e32 v74, 1, v77
	v_fma_f32 v75, -v73, v77, v70
	v_fma_f32 v76, -v74, v77, v70
	v_cmp_ge_f32_e64 s[56:57], 0, v75
	v_cndmask_b32_e64 v71, v71, v72, s[40:41]
	s_mov_b32 s17, 0xbfb8aa3b
	v_cndmask_b32_e64 v73, v77, v73, s[56:57]
	v_cmp_lt_f32_e64 s[56:57], 0, v76
	s_nop 1
	v_cndmask_b32_e64 v73, v73, v74, s[56:57]
	v_mul_f32_e32 v74, 0x37800000, v73
	v_cndmask_b32_e32 v73, v73, v74, vcc
	v_cmp_class_f32_e32 vcc, v70, v92
	s_nop 1
	v_cndmask_b32_e32 v70, v73, v70, vcc
	v_div_scale_f32 v73, s[18:19], v70, v70, 1.0
	v_rcp_f32_e32 v74, v73
	v_div_scale_f32 v72, vcc, 1.0, v70, 1.0
	v_fma_f32 v75, -v73, v74, 1.0
	v_fmac_f32_e32 v74, v75, v74
	v_mul_f32_e32 v75, v72, v74
	v_fma_f32 v76, -v73, v75, v72
	v_fmac_f32_e32 v75, v76, v74
	v_fma_f32 v72, -v73, v75, v72
	v_div_fmas_f32 v72, v72, v74, v75
	v_div_fixup_f32 v70, v72, v70, 1.0
	s_waitcnt lgkmcnt(0)
	v_fmac_f32_e32 v79, v70, v71
	s_waitcnt lgkmcnt(0)
	v_add_f32_e32 v70, v79, v80
	v_mul_f32_e64 v71, |v70|, s17
	v_exp_f32_e32 v71, v71
	s_nop 0
	v_add_f32_e32 v72, 1.0, v71
	v_cmp_neq_f32_e32 vcc, 1.0, v72
	s_and_saveexec_b64 s[22:23], vcc
	s_cbranch_execz .LBB0_415
	v_cmp_gt_f32_e32 vcc, s9, v72
	s_nop 1
	v_cndmask_b32_e64 v73, 0, 32, vcc
	v_ldexp_f32 v73, v72, v73
	v_log_f32_e32 v73, v73
	v_add_f32_e32 v72, -1.0, v72
	v_div_scale_f32 v75, s[18:19], v72, v72, v71
	v_mul_f32_e32 v74, 0x3f317217, v73
	v_fma_f32 v74, v73, s15, -v74
	v_rcp_f32_e32 v76, v75
	v_fmac_f32_e32 v74, 0x3377d1cf, v73
	v_fmac_f32_e32 v74, 0x3f317217, v73
	v_cmp_lt_f32_e64 s[56:57], |v73|, s16
	s_nop 1
	v_cndmask_b32_e64 v73, v73, v74, s[56:57]
	v_cndmask_b32_e32 v74, 0, v93, vcc
	v_sub_f32_e32 v73, v73, v74
	v_fma_f32 v74, -v75, v76, 1.0
	v_fmac_f32_e32 v76, v74, v76
	v_div_scale_f32 v74, vcc, v71, v72, v71
	v_mul_f32_e32 v77, v74, v76
	v_fma_f32 v78, -v75, v77, v74
	v_fmac_f32_e32 v77, v78, v76
	v_fma_f32 v74, -v75, v77, v74
	v_div_fmas_f32 v74, v74, v76, v77
	v_div_fixup_f32 v71, v74, v72, v71
	v_mul_f32_e32 v71, v73, v71
	s_branch .LBB0_415
.LBB0_420:
	s_waitcnt vmcnt(0) lgkmcnt(0)
	s_barrier
	v_mov_b32_e32 v14, v254
	s_cmpk_lt_i32 s3, 0x600
	s_movk_i32 s9, 0x400
	v_readfirstlane_b32 s8, v14
	s_cselect_b64 s[6:7], -1, 0
	s_cmpk_gt_i32 s3, 0x5ff
	s_cbranch_scc0 .LBB0_423
	s_andn2_b64 vcc, exec, s[6:7]
	s_cbranch_vccz .LBB0_424
